# tile-scheduler r/gsz division replaced by shifts (gsz==4 for nM=64) in P2/P4/P9 unit loops, padded to the old code size, on top of v129
# baseline (speedup 1.0000x reference)
.LBB0_122:
	s_add_i32 s86, s86, 1
	s_mul_i32 s2, s86, s89
	s_mul_hi_u32 s3, s86, s33
	s_add_i32 s3, s3, s2
	s_mul_i32 s2, s86, s33
	s_add_u32 s30, s2, s10
	s_addc_u32 s31, s3, s81
	v_cmp_gt_i64_e32 vcc, s[30:31], v[132:133]
	v_cmp_lt_i64_e64 s[2:3], s[30:31], v[130:131]
	s_cbranch_vccnz .LBB0_124
	s_ashr_i32 s8, s30, 31
	s_lshr_b32 s8, s8, 29
	s_add_i32 s8, s30, s8
	s_ashr_i32 s9, s8, 3
	s_and_b32 s8, s8, -8
	s_sub_i32 s8, s30, s8
	s_cmp_lt_i32 s8, 0
	s_cselect_b32 s11, s82, 0xb0
	s_mul_i32 s8, s8, s11
	s_add_i32 s8, s8, s9
	s_mul_hi_i32 s9, s8, 0x2e8ba2e9
	s_lshr_b32 s11, s9, 31
	s_ashr_i32 s9, s9, 4
	s_add_i32 s9, s9, s11
	s_lshl_b32 s11, s9, 2
	s_mulk_i32 s9, 0x58
	s_sub_i32 s8, s8, s9
	s_lshr_b32 s20, s8, 2
	s_and_b32 s8, s8, 3
	s_add_i32 s28, s11, s8
	s_nop 0
	s_nop 0
	s_nop 0
	s_nop 0
	s_nop 0
	s_nop 0
	s_nop 0
	s_nop 0
	s_nop 0
	s_nop 0
	s_nop 0
	s_nop 0
	s_nop 0
	s_nop 0
	s_nop 0
	s_nop 0
	s_nop 0
	s_nop 0
	s_nop 0
	s_nop 0
	s_nop 0
	s_nop 0
	s_nop 0
	s_nop 0
	s_nop 0
	s_nop 0
	s_nop 0
	s_nop 0
	s_nop 0
	s_nop 0

.LBB0_325:
	s_add_i32 s88, s88, 1
	s_mul_i32 s2, s88, s91
	s_mul_hi_u32 s3, s88, s33
	s_add_i32 s3, s3, s2
	s_mul_i32 s2, s88, s33
	s_add_u32 s64, s2, s10
	s_addc_u32 s65, s3, s82
	v_cmp_gt_i64_e32 vcc, s[64:65], v[132:133]
	v_cmp_lt_i64_e64 s[2:3], s[64:65], v[130:131]
	s_cbranch_vccnz .LBB0_327
	s_ashr_i32 s8, s64, 31
	s_lshr_b32 s8, s8, 29
	s_add_i32 s8, s64, s8
	s_ashr_i32 s9, s8, 3
	s_and_b32 s8, s8, -8
	s_sub_i32 s8, s64, s8
	s_cmp_lt_i32 s8, 0
	s_cselect_b32 s11, s83, 0x60
	s_mul_i32 s8, s8, s11
	s_add_i32 s8, s8, s9
	s_mul_hi_i32 s9, s8, 0x2aaaaaab
	s_lshr_b32 s11, s9, 31
	s_ashr_i32 s9, s9, 3
	s_add_i32 s9, s9, s11
	s_lshl_b32 s11, s9, 2
	s_mul_i32 s9, s9, 48
	s_sub_i32 s8, s8, s9
	s_lshr_b32 s20, s8, 2
	s_and_b32 s8, s8, 3
	s_add_i32 s26, s11, s8
	s_nop 0
	s_nop 0
	s_nop 0
	s_nop 0
	s_nop 0
	s_nop 0
	s_nop 0
	s_nop 0
	s_nop 0
	s_nop 0
	s_nop 0
	s_nop 0
	s_nop 0
	s_nop 0
	s_nop 0
	s_nop 0
	s_nop 0
	s_nop 0
	s_nop 0
	s_nop 0
	s_nop 0
	s_nop 0
	s_nop 0
	s_nop 0
	s_nop 0
	s_nop 0
	s_nop 0
	s_nop 0
	s_nop 0
	s_nop 0

.LBB0_616:
	s_add_i32 s68, s68, 1
	s_mul_i32 s2, s68, s71
	s_mul_hi_u32 s3, s68, s33
	s_add_i32 s3, s3, s2
	s_mul_i32 s2, s68, s33
	s_add_u32 s26, s2, s10
	s_addc_u32 s27, s3, s63
	v_cmp_gt_i64_e32 vcc, s[26:27], v[132:133]
	v_cmp_lt_i64_e64 s[2:3], s[26:27], v[130:131]
	s_cbranch_vccnz .LBB0_618
	s_ashr_i32 s8, s26, 31
	s_lshr_b32 s8, s8, 29
	s_add_i32 s8, s26, s8
	s_ashr_i32 s9, s8, 3
	s_and_b32 s8, s8, -8
	s_sub_i32 s8, s26, s8
	s_cmp_lt_i32 s8, 0
	s_cselect_b32 s11, s64, 0xb0
	s_mul_i32 s8, s8, s11
	s_add_i32 s8, s8, s9
	s_mul_hi_i32 s9, s8, 0x2e8ba2e9
	s_lshr_b32 s11, s9, 31
	s_ashr_i32 s9, s9, 4
	s_add_i32 s9, s9, s11
	s_lshl_b32 s11, s9, 2
	s_mulk_i32 s9, 0x58
	s_sub_i32 s8, s8, s9
	s_lshr_b32 s18, s8, 2
	s_and_b32 s8, s8, 3
	s_add_i32 s20, s11, s8
	s_nop 0
	s_nop 0
	s_nop 0
	s_nop 0
	s_nop 0
	s_nop 0
	s_nop 0
	s_nop 0
	s_nop 0
	s_nop 0
	s_nop 0
	s_nop 0
	s_nop 0
	s_nop 0
	s_nop 0
	s_nop 0
	s_nop 0
	s_nop 0
	s_nop 0
	s_nop 0
	s_nop 0
	s_nop 0
	s_nop 0
	s_nop 0
	s_nop 0
	s_nop 0
	s_nop 0
	s_nop 0
	s_nop 0
	s_nop 0
